# nt cache hint on the streamed weight-operand LDS-DMA loads in the ffn1 and inproj K loops (activations keep default policy), on v27
# baseline (speedup 1.0000x reference)
.LBB0_197:
	s_andn2_b64 vcc, exec, s[14:15]
	s_cbranch_vccnz .LBB0_192
	s_add_i32 s14, s16, 0x8000
	s_and_b32 s14, s14, 0x8000
	v_add_u32_e32 v94, s14, v85
	v_lshl_add_u64 v[90:91], v[80:81], 0, s[22:23]
	v_readfirstlane_b32 s14, v94
	s_mov_b32 m0, s14
	v_lshl_add_u64 v[92:93], v[90:91], 0, s[64:65]
	s_mov_b64 s[14:15], 0x10000
	global_load_lds_dwordx4 v[92:93], off
	s_add_u32 m0, m0, 0x1000
	v_lshl_add_u64 v[92:93], v[92:93], 0, s[14:15]
	global_load_lds_dwordx4 v[92:93], off
	s_add_u32 m0, m0, 0x1000
	v_lshl_add_u64 v[92:93], v[92:93], 0, s[14:15]
	global_load_lds_dwordx4 v[92:93], off
	s_add_u32 m0, m0, 0x1000
	v_lshl_add_u64 v[92:93], v[92:93], 0, s[14:15]
	global_load_lds_dwordx4 v[92:93], off
	s_add_u32 m0, m0, 0x1000
	v_lshl_add_u64 v[90:91], v[82:83], 0, s[22:23]
	s_mov_b64 s[14:15], 0x201080
	v_lshl_add_u64 v[92:93], v[90:91], 0, s[14:15]
	s_mov_b64 s[14:15], 0x10000
	global_load_lds_dwordx4 v[92:93], off nt
	s_add_u32 m0, m0, 0x1000
	v_lshl_add_u64 v[92:93], v[92:93], 0, s[14:15]
	global_load_lds_dwordx4 v[92:93], off nt
	s_add_u32 m0, m0, 0x1000
	v_lshl_add_u64 v[92:93], v[92:93], 0, s[14:15]
	global_load_lds_dwordx4 v[92:93], off nt
	s_add_u32 m0, m0, 0x1000
	v_lshl_add_u64 v[92:93], v[92:93], 0, s[14:15]
	global_load_lds_dwordx4 v[92:93], off nt
	s_branch .LBB0_192

.LBB0_550:
	s_andn2_b64 vcc, exec, s[14:15]
	s_cbranch_vccnz .LBB0_545
	s_add_i32 s14, s16, 0x8000
	s_and_b32 s14, s14, 0x8000
	v_add_u32_e32 v94, s14, v85
	v_lshl_add_u64 v[90:91], v[82:83], 0, s[8:9]
	v_readfirstlane_b32 s14, v94
	s_mov_b32 m0, s14
	v_lshl_add_u64 v[92:93], v[90:91], 0, s[64:65]
	s_mov_b64 s[14:15], 0x10000
	global_load_lds_dwordx4 v[92:93], off
	s_add_u32 m0, m0, 0x1000
	v_lshl_add_u64 v[92:93], v[92:93], 0, s[14:15]
	global_load_lds_dwordx4 v[92:93], off
	s_add_u32 m0, m0, 0x1000
	v_lshl_add_u64 v[92:93], v[92:93], 0, s[14:15]
	global_load_lds_dwordx4 v[92:93], off
	s_add_u32 m0, m0, 0x1000
	v_lshl_add_u64 v[92:93], v[92:93], 0, s[14:15]
	global_load_lds_dwordx4 v[92:93], off
	s_add_u32 m0, m0, 0x1000
	v_lshl_add_u64 v[90:91], v[80:81], 0, s[8:9]
	v_lshl_add_u64 v[92:93], v[90:91], 0, s[50:51]
	s_mov_b64 s[14:15], 0x10000
	global_load_lds_dwordx4 v[92:93], off nt
	s_add_u32 m0, m0, 0x1000
	v_lshl_add_u64 v[92:93], v[92:93], 0, s[14:15]
	global_load_lds_dwordx4 v[92:93], off nt
	s_add_u32 m0, m0, 0x1000
	v_lshl_add_u64 v[92:93], v[92:93], 0, s[14:15]
	global_load_lds_dwordx4 v[92:93], off nt
	s_add_u32 m0, m0, 0x1000
	v_lshl_add_u64 v[92:93], v[92:93], 0, s[14:15]
	global_load_lds_dwordx4 v[92:93], off nt
	s_branch .LBB0_545
